# grid barrier: wait for the arrive atomic return with vmcnt(1) while the early invalidate stays in flight
# baseline (speedup 1.0000x reference)
; __device__ __forceinline__ unsigned xb_ld(unsigned* p)              { return __hip_atomic_load(p, __ATOMIC_RELAXED, __HIP_MEMORY_SCOPE_AGENT); }
; __device__ __forceinline__ unsigned xb_add(unsigned* p, unsigned v) { return __hip_atomic_fetch_add(p, v, __ATOMIC_RELAXED, __HIP_MEMORY_SCOPE_AGENT); }
; #define XB_SPIN(cond, bar) do { unsigned _sp = 0; while (cond) { __builtin_amdgcn_s_sleep(1); \
;     if ((++_sp & 255u) == 0u) { if (xb_ld(&(bar)[XB_TMO])) break; if (_sp > XB_SPIN_CAP) { atomicAdd(&(bar)[XB_TMO], 1u); break; } } } } while (0)
; __device__ __forceinline__ void xcd_barrier(const XcdBarrier& b) {
;     ...
;         unsigned nloc = b.st[0], nx = b.st[1];
;         if (nloc == 0u) { xcd_barrier_complete(bar, b.x, nloc, nx); b.st[0] = nloc; b.st[1] = nx; }
;         const unsigned old = xb_add(&bar[XB_XSUB(b.x)], 1u);
;         const unsigned gen = old / nloc;
;         if (old + 1u == (gen + 1u) * nloc) {
;             __builtin_amdgcn_fence(__ATOMIC_RELEASE, "agent");
;             asm volatile("s_waitcnt vmcnt(0)" ::: "memory");
;             const unsigned og = xb_add(&bar[XB_TOP], 1u);
;             const unsigned tg = og / nx;
;             if (og + 1u == (tg + 1u) * nx) xb_add(&bar[XB_TOPGEN], 1u);
;             else XB_SPIN(xb_ld(&bar[XB_TOPGEN]) == tg, bar);
;             __builtin_amdgcn_fence(__ATOMIC_ACQUIRE, "agent");
;             asm volatile("s_waitcnt vmcnt(0)" ::: "memory");
;         } else {
;             XB_SPIN(xb_ld(&bar[XB_TOPGEN]) == gen, bar);
.LBB0_93:
	s_lshl_b32 s3, s2, 8
	v_readlane_b32 s4, v252, 8
	v_readlane_b32 s5, v252, 9
	s_add_u32 s4, s4, s3
	s_addc_u32 s5, s5, 0
	v_mov_b32_e32 v2, 0x1000
	v_mov_b32_e32 v4, 1
	v_sub_u32_e32 v5, 0, v3
	global_atomic_add v4, v2, v4, s[4:5] offset:1024 sc0
	buffer_inv sc1
	v_cvt_f32_u32_e32 v2, v3
	v_rcp_iflag_f32_e32 v2, v2
	s_nop 0
	v_mul_f32_e32 v2, 0x4f7ffffe, v2
	v_cvt_u32_f32_e32 v2, v2
	v_mul_lo_u32 v5, v5, v2
	v_mul_hi_u32 v5, v2, v5
	v_add_u32_e32 v2, v2, v5
	s_waitcnt vmcnt(1)
	v_mul_hi_u32 v2, v4, v2
	v_mul_lo_u32 v5, v2, v3
	v_sub_u32_e32 v5, v4, v5
	v_add_u32_e32 v6, 1, v2
	v_cmp_ge_u32_e32 vcc, v5, v3
	v_add_u32_e32 v4, 1, v4
	s_nop 0
	v_cndmask_b32_e32 v2, v2, v6, vcc
	v_sub_u32_e32 v6, v5, v3
	v_cndmask_b32_e32 v5, v5, v6, vcc
	v_add_u32_e32 v6, 1, v2
	v_cmp_ge_u32_e32 vcc, v5, v3
	s_nop 1
	v_cndmask_b32_e32 v2, v2, v6, vcc
	v_mul_lo_u32 v5, v3, v2
	v_add_u32_e32 v3, v5, v3
	v_cmp_ne_u32_e32 vcc, v4, v3
	s_and_saveexec_b64 s[4:5], vcc
	s_xor_b64 s[4:5], exec, s[4:5]
	s_cbranch_execz .LBB0_107
	v_readlane_b32 s6, v252, 8
	s_waitcnt lgkmcnt(0)
	v_mov_b32_e32 v1, 0x3000
	v_readlane_b32 s7, v252, 9
	s_add_u32 s8, s6, 0x3500
	s_addc_u32 s9, s7, 0
	s_nop 2
	global_load_dword v1, v1, s[6:7] offset:1280 sc1
	s_waitcnt vmcnt(0)
	v_cmp_eq_u32_e32 vcc, v1, v2
	s_and_saveexec_b64 s[6:7], vcc
	s_cbranch_execz .LBB0_106
	s_mov_b32 s3, 1
	s_mov_b64 s[10:11], 0
	v_mov_b32_e32 v1, 0
	s_branch .LBB0_97

; __device__ __forceinline__ unsigned xb_ld(unsigned* p)              { return __hip_atomic_load(p, __ATOMIC_RELAXED, __HIP_MEMORY_SCOPE_AGENT); }
; __device__ __forceinline__ unsigned xb_add(unsigned* p, unsigned v) { return __hip_atomic_fetch_add(p, v, __ATOMIC_RELAXED, __HIP_MEMORY_SCOPE_AGENT); }
; #define XB_SPIN(cond, bar) do { unsigned _sp = 0; while (cond) { __builtin_amdgcn_s_sleep(1); \
;     if ((++_sp & 255u) == 0u) { if (xb_ld(&(bar)[XB_TMO])) break; if (_sp > XB_SPIN_CAP) { atomicAdd(&(bar)[XB_TMO], 1u); break; } } } } while (0)
; __device__ __forceinline__ void xcd_barrier(const XcdBarrier& b) {
;     ...
;         unsigned nloc = b.st[0], nx = b.st[1];
;         if (nloc == 0u) { xcd_barrier_complete(bar, b.x, nloc, nx); b.st[0] = nloc; b.st[1] = nx; }
;         const unsigned old = xb_add(&bar[XB_XSUB(b.x)], 1u);
;         const unsigned gen = old / nloc;
;         if (old + 1u == (gen + 1u) * nloc) {
;             __builtin_amdgcn_fence(__ATOMIC_RELEASE, "agent");
;             asm volatile("s_waitcnt vmcnt(0)" ::: "memory");
;             const unsigned og = xb_add(&bar[XB_TOP], 1u);
;             const unsigned tg = og / nx;
;             if (og + 1u == (tg + 1u) * nx) xb_add(&bar[XB_TOPGEN], 1u);
;             else XB_SPIN(xb_ld(&bar[XB_TOPGEN]) == tg, bar);
;             __builtin_amdgcn_fence(__ATOMIC_ACQUIRE, "agent");
;             asm volatile("s_waitcnt vmcnt(0)" ::: "memory");
;         } else {
;             XB_SPIN(xb_ld(&bar[XB_TOPGEN]) == gen, bar);
.LBB0_333:
	v_readlane_b32 s4, v253, 35
	v_readlane_b32 s5, v253, 36
	v_cvt_f32_u32_e32 v1, v2
	v_sub_u32_e32 v4, 0, v2
	v_rcp_iflag_f32_e32 v1, v1
	s_nop 1
	global_atomic_add v3, v177, v238, s[4:5] sc0
	buffer_inv sc1
	v_mul_f32_e32 v1, 0x4f7ffffe, v1
	v_cvt_u32_f32_e32 v1, v1
	v_mul_lo_u32 v4, v4, v1
	v_mul_hi_u32 v4, v1, v4
	v_add_u32_e32 v1, v1, v4
	s_waitcnt vmcnt(1)
	v_mul_hi_u32 v1, v3, v1
	v_mul_lo_u32 v4, v1, v2
	v_sub_u32_e32 v4, v3, v4
	v_add_u32_e32 v5, 1, v1
	v_cmp_ge_u32_e32 vcc, v4, v2
	v_add_u32_e32 v3, 1, v3
	s_nop 0
	v_cndmask_b32_e32 v1, v1, v5, vcc
	v_sub_u32_e32 v5, v4, v2
	v_cndmask_b32_e32 v4, v4, v5, vcc
	v_add_u32_e32 v5, 1, v1
	v_cmp_ge_u32_e32 vcc, v4, v2
	s_nop 1
	v_cndmask_b32_e32 v1, v1, v5, vcc
	v_mul_lo_u32 v4, v2, v1
	v_add_u32_e32 v2, v4, v2
	v_cmp_ne_u32_e32 vcc, v3, v2
	s_and_saveexec_b64 s[4:5], vcc
	s_xor_b64 s[4:5], exec, s[4:5]
	s_cbranch_execz .LBB0_347
	v_readlane_b32 s8, v253, 37
	v_readlane_b32 s9, v253, 38
	s_waitcnt lgkmcnt(0)
	s_nop 3
	global_load_dword v0, v177, s[8:9] sc1
	s_waitcnt vmcnt(0)
	v_cmp_eq_u32_e32 vcc, v0, v1
	s_and_saveexec_b64 s[8:9], vcc
	s_cbranch_execz .LBB0_346
	s_mov_b32 s3, 1
	s_mov_b64 s[16:17], 0
	s_branch .LBB0_337

; __device__ __forceinline__ unsigned xb_ld(unsigned* p)              { return __hip_atomic_load(p, __ATOMIC_RELAXED, __HIP_MEMORY_SCOPE_AGENT); }
; __device__ __forceinline__ unsigned xb_add(unsigned* p, unsigned v) { return __hip_atomic_fetch_add(p, v, __ATOMIC_RELAXED, __HIP_MEMORY_SCOPE_AGENT); }
; #define XB_SPIN(cond, bar) do { unsigned _sp = 0; while (cond) { __builtin_amdgcn_s_sleep(1); \
;     if ((++_sp & 255u) == 0u) { if (xb_ld(&(bar)[XB_TMO])) break; if (_sp > XB_SPIN_CAP) { atomicAdd(&(bar)[XB_TMO], 1u); break; } } } } while (0)
; __device__ __forceinline__ void xcd_barrier(const XcdBarrier& b) {
;     ...
;         unsigned nloc = b.st[0], nx = b.st[1];
;         if (nloc == 0u) { xcd_barrier_complete(bar, b.x, nloc, nx); b.st[0] = nloc; b.st[1] = nx; }
;         const unsigned old = xb_add(&bar[XB_XSUB(b.x)], 1u);
;         const unsigned gen = old / nloc;
;         if (old + 1u == (gen + 1u) * nloc) {
;             __builtin_amdgcn_fence(__ATOMIC_RELEASE, "agent");
;             asm volatile("s_waitcnt vmcnt(0)" ::: "memory");
;             const unsigned og = xb_add(&bar[XB_TOP], 1u);
;             const unsigned tg = og / nx;
;             if (og + 1u == (tg + 1u) * nx) xb_add(&bar[XB_TOPGEN], 1u);
;             else XB_SPIN(xb_ld(&bar[XB_TOPGEN]) == tg, bar);
;             __builtin_amdgcn_fence(__ATOMIC_ACQUIRE, "agent");
;             asm volatile("s_waitcnt vmcnt(0)" ::: "memory");
;         } else {
;             XB_SPIN(xb_ld(&bar[XB_TOPGEN]) == gen, bar);
.LBB0_509:
	v_readlane_b32 s4, v253, 35
	v_readlane_b32 s5, v253, 36
	v_cvt_f32_u32_e32 v1, v2
	v_sub_u32_e32 v4, 0, v2
	v_rcp_iflag_f32_e32 v1, v1
	s_nop 1
	global_atomic_add v3, v177, v238, s[4:5] sc0
	buffer_inv sc1
	v_mul_f32_e32 v1, 0x4f7ffffe, v1
	v_cvt_u32_f32_e32 v1, v1
	v_mul_lo_u32 v4, v4, v1
	v_mul_hi_u32 v4, v1, v4
	v_add_u32_e32 v1, v1, v4
	s_waitcnt vmcnt(1)
	v_mul_hi_u32 v1, v3, v1
	v_mul_lo_u32 v4, v1, v2
	v_sub_u32_e32 v4, v3, v4
	v_add_u32_e32 v5, 1, v1
	v_cmp_ge_u32_e32 vcc, v4, v2
	v_add_u32_e32 v3, 1, v3
	s_nop 0
	v_cndmask_b32_e32 v1, v1, v5, vcc
	v_sub_u32_e32 v5, v4, v2
	v_cndmask_b32_e32 v4, v4, v5, vcc
	v_add_u32_e32 v5, 1, v1
	v_cmp_ge_u32_e32 vcc, v4, v2
	s_nop 1
	v_cndmask_b32_e32 v1, v1, v5, vcc
	v_mul_lo_u32 v4, v2, v1
	v_add_u32_e32 v2, v4, v2
	v_cmp_ne_u32_e32 vcc, v3, v2
	s_and_saveexec_b64 s[4:5], vcc
	s_xor_b64 s[4:5], exec, s[4:5]
	s_cbranch_execz .LBB0_523
	v_readlane_b32 s6, v253, 37
	v_readlane_b32 s7, v253, 38
	s_waitcnt lgkmcnt(0)
	s_nop 3
	global_load_dword v0, v177, s[6:7] sc1
	s_waitcnt vmcnt(0)
	v_cmp_eq_u32_e32 vcc, v0, v1
	s_and_saveexec_b64 s[6:7], vcc
	s_cbranch_execz .LBB0_522
	s_mov_b32 s3, 1
	s_mov_b64 s[8:9], 0
	s_branch .LBB0_513
